# phase-2 static rebalance: WGs 128/129 (prompt cumsum units) skip 11 pass-A rounds, 22 other WGs take them
# speedup vs baseline: 1.1534x; 1.1001x over previous
.LBB0_357:
	s_add_u32 s0, s76, 0x10243500
	v_writelane_b32 v255, s0, 7
	s_addc_u32 s0, s77, 0
	v_writelane_b32 v255, s0, 8
	s_add_u32 s0, s76, 0x8100000
	v_readlane_b32 s4, v254, 34
	v_writelane_b32 v255, s0, 9
	s_addc_u32 s0, s77, 0
	s_lshl_b32 s5, s80, 4
	s_and_b32 s28, s4, 0xffffffc0
	v_writelane_b32 v255, s0, 10
	s_add_u32 s0, s76, 0x10100000
	v_writelane_b32 v255, s0, 1
	s_addc_u32 s0, s77, 0
	v_writelane_b32 v255, s0, 3
	s_add_u32 s0, s76, 0x10343500
	v_writelane_b32 v255, s0, 4
	s_addc_u32 s0, s77, 0
	s_lshl_b32 s93, s80, 2
	v_writelane_b32 v255, s0, 11
	s_add_u32 s0, s78, 0xa81000
	v_writelane_b32 v255, s0, 12
	s_addc_u32 s0, s79, 0
	v_writelane_b32 v255, s0, 13
	s_add_u32 s0, s78, 0xb81000
	v_writelane_b32 v255, s0, 14
	s_addc_u32 s0, s79, 0
	v_writelane_b32 v255, s0, 15
	s_lshl_b32 s0, s80, 5
	s_and_b32 s23, s0, 32
	s_add_u32 s48, s78, 0x10c9000
	s_addc_u32 s49, s79, 0
	s_add_u32 s0, s78, 0x1e467000
	v_writelane_b32 v255, s0, 16
	s_addc_u32 s0, s79, 0
	v_readlane_b32 s52, v254, 2
	v_writelane_b32 v255, s0, 17
	s_add_u32 s0, s78, 0xc89000
	v_readlane_b32 s56, v254, 6
	v_readlane_b32 s57, v254, 7
	v_writelane_b32 v255, s0, 18
	s_addc_u32 s0, s79, 0
	s_lshl_b32 s22, s80, 3
	v_readlane_b32 s58, v254, 8
	v_readlane_b32 s59, v254, 9
	v_readlane_b32 s60, v254, 10
	v_readlane_b32 s61, v254, 11
	v_readlane_b32 s62, v254, 12
	v_readlane_b32 s63, v254, 13
	v_readlane_b32 s64, v254, 14
	v_readlane_b32 s65, v254, 15
	v_readlane_b32 s66, v254, 16
	v_readlane_b32 s67, v254, 17
	s_mov_b64 s[8:9], s[56:57]
	v_writelane_b32 v255, s0, 19
	s_add_u32 s0, s8, 0x1800
	s_addc_u32 s1, s9, 0
	v_readlane_b32 s53, v254, 3
	v_readlane_b32 s54, v254, 4
	v_readlane_b32 s55, v254, 5
	v_writelane_b32 v254, s0, 51
	s_mov_b32 s3, 0xc300
	s_movk_i32 s85, 0x7ff
	v_writelane_b32 v254, s1, 52
	s_add_u32 s0, s8, 0x1000
	s_addc_u32 s1, s9, 0
	v_writelane_b32 v254, s0, 53
	s_and_b32 s29, s22, 0x1ffffff0
	s_waitcnt vmcnt(3)
	v_mbcnt_lo_u32_b32 v0, -1, 0
	v_writelane_b32 v254, s1, 54
	s_add_u32 s0, s78, 0x1cb31000
	v_writelane_b32 v254, s0, 55
	s_addc_u32 s0, s79, 0
	s_lshl_b32 s2, s80, 8
	v_writelane_b32 v254, s0, 57
	s_add_i32 s0, s2, 0x19600
	s_cmp_eq_u32 s80, 7
	v_writelane_b32 v254, s0, 59
	s_cselect_b64 s[0:1], -1, 0
	v_writelane_b32 v254, s0, 61
	v_mov_b32_e32 v1, 0
	s_mov_b32 s91, 0xbfb8aa3b
	v_writelane_b32 v254, s1, 62
	s_lshl_b32 s0, s80, 1
	s_and_b32 s0, s0, 2
	s_lshl_b32 s24, s0, 4
	s_lshl_b32 s0, s0, 6
	s_mov_b32 s51, s0
	s_or_b32 s0, s0, 0x1c700
	v_writelane_b32 v254, s0, 63
	s_cmpk_lt_u32 s4, 0x80
	v_readlane_b32 s0, v254, 42
	v_readlane_b32 s1, v254, 43
	s_cselect_b64 s[70:71], -1, 0
	s_and_b64 s[0:1], s[0:1], exec
	s_cselect_b32 s21, s3, 0x14500
	s_lshl_b32 s0, s80, 6
	s_add_i32 s0, s21, s0
	v_writelane_b32 v255, s0, 20
	s_add_u32 s0, s78, 0x18931000
	v_writelane_b32 v254, s0, 45
	s_addc_u32 s0, s79, 0
	v_writelane_b32 v254, s0, 47
	s_add_i32 s0, s80, -1
	s_bfe_u32 s35, s4, 0x30006
	s_cmp_gt_u32 s0, 6
	s_cselect_b64 s[72:73], -1, 0
	s_and_b32 s84, s80, 0x3fffff8
	s_cmp_lg_u32 s35, 0
	s_cselect_b64 s[30:31], -1, 0
	v_writelane_b32 v255, s5, 21
	s_add_i32 s0, s5, 0xfffff800
	v_writelane_b32 v255, s0, 22
	s_lshr_b32 s0, s4, 2
	s_and_b32 s0, s0, 0x3ffffff0
	v_writelane_b32 v255, s0, 23
	s_add_i32 s0, s28, 0xfffffe00
	v_writelane_b32 v255, s0, 24
	s_add_i32 s0, s2, 0x8200
	v_readlane_b32 s2, v254, 44
	v_writelane_b32 v255, s0, 25
	s_mov_b32 s68, 0xb2a5705f
	s_mov_b32 s69, 0x42ce8ed0
	s_mov_b32 s97, 0xc2b17218
	s_mov_b32 s81, 0x7f800000
	s_mov_b32 s34, 0x3f2aaaab
	v_mov_b32_e32 v112, 0x3ecc95a3
	s_mov_b32 s0, 0x33800000
	s_movk_i32 s1, 0xd40
	s_movk_i32 s25, 0x104
	s_mov_b32 s95, 0x800000
	v_mov_b32_e32 v113, 0x7f800000
	v_mov_b32_e32 v90, 0x3f317218
	v_mbcnt_hi_u32_b32 v114, -1, v0
	v_mov_b32_e32 v115, 0x41b17218
	v_mov_b32_e32 v116, 0x24900
	v_mov_b32_e32 v117, 0x900
	v_mov_b32_e32 v118, 0x20800
	s_mov_b32 s50, 0x3f317217
	s_mov_b32 s89, 0
	s_mov_b32 s90, 0x3e9b6dac
	s_mov_b32 s92, 0x3f317218
	s_mov_b32 s94, 0xb102e308
	s_mov_b32 s96, 0x3f2aaada
	s_mov_b32 s26, s2
	s_mov_b32 s3, 0
	s_cmpk_lg_u32 s20, 0x100
	s_cbranch_scc1 .Lp2_init_done
	s_and_b32 s3, s2, 0xfe
	s_cmpk_eq_u32 s3, 0x80
	s_cselect_b32 s3, 1, 0
	s_cbranch_scc1 .Lp2_init_done
	s_cmpk_lt_u32 s2, 0xa8
	s_cbranch_scc1 .Lp2_init_done
	s_and_b32 vcc_lo, s2, 6
	s_cmp_lg_u32 vcc_lo, 0
	s_cbranch_scc1 .Lp2_init_done
	s_sub_u32 vcc_lo, s2, 0xa8
	s_lshr_b32 vcc_lo, vcc_lo, 3
	s_cmp_ge_u32 vcc_lo, 11
	s_cbranch_scc1 .Lp2_init_done
	s_add_u32 vcc_lo, vcc_lo, 5
	s_lshl_b32 vcc_lo, vcc_lo, 8
	s_and_b32 s3, s2, 1
	s_add_u32 vcc_lo, vcc_lo, s3
	s_add_u32 s26, vcc_lo, 0x80
	s_mov_b32 s3, 2
.Lp2_init_done:
	s_nop 3
	v_writelane_b32 v255, s3, 40
	s_mov_b64 s[10:11], s[58:59]
	s_mov_b64 s[12:13], s[60:61]
	s_mov_b64 s[14:15], s[62:63]
	s_mov_b64 s[16:17], s[64:65]
	s_mov_b64 s[18:19], s[66:67]
	s_branch .LBB0_360

.LBB0_359:
	v_readlane_b32 s2, v255, 40
	s_cmp_eq_u32 s2, 0
	s_cbranch_scc1 .Lp2_norm
	s_cmp_eq_u32 s2, 2
	s_cbranch_scc1 .Lp2_recv
	s_lshr_b32 s2, s26, 8
	s_cmp_eq_u32 s2, 4
	s_cbranch_scc0 .Lp2_norm
	s_addk_i32 s26, 2816
	s_branch .Lp2_norm
.Lp2_recv:
	v_readlane_b32 s26, v254, 44
	s_mov_b32 s2, 0
	s_nop 3
	v_writelane_b32 v255, s2, 40
	s_branch .LBB0_360
